# v040 with s_setprio flips removed and one static priority raise for the wave half that skips the extra stagger barrier
# speedup vs baseline: 1.0112x; 1.0112x over previous
.LBB0_124:
	s_andn2_b64 vcc, exec, s[0:1]
	s_cbranch_vccnz .LBB0_170
	v_bfe_i32 v4, v2, 27, 1
	v_lshlrev_b32_e32 v6, 4, v2
	v_lshrrev_b32_e32 v4, 22, v4
	v_ashrrev_i32_e32 v3, 31, v2
	v_add_u32_e32 v4, v6, v4
	v_lshrrev_b32_e32 v3, 26, v3
	v_and_b32_e32 v4, 0xfffffc00, v4
	v_add_u32_e32 v3, v2, v3
	v_sub_u32_e32 v4, v6, v4
	v_ashrrev_i32_e32 v3, 6, v3
	v_lshrrev_b32_e32 v5, 4, v4
	v_bitop3_b32 v5, v5, v4, 32 bitop3:0x6c
	v_lshlrev_b32_e32 v4, 3, v3
	v_and_b32_e32 v7, -16, v4
	v_ashrrev_i32_e32 v4, 31, v5
	v_lshrrev_b32_e32 v4, 26, v4
	v_add_u32_e32 v8, v5, v4
	v_ashrrev_i32_e32 v4, 6, v8
	v_and_b32_e32 v8, 0xc0, v8
	v_sub_u32_e32 v5, v5, v8
	v_lshlrev_b32_e32 v9, 5, v3
	v_ashrrev_i16_sdwa v5, v231, sext(v5) dst_sel:DWORD dst_unused:UNUSED_PAD src0_sel:DWORD src1_sel:BYTE_0
	v_and_b32_e32 v9, 32, v9
	v_bfe_i32 v5, v5, 0, 16
	v_add_u32_e32 v7, v4, v7
	v_and_b32_e32 v11, 3, v4
	s_mov_b32 s1, 0xfffe0
	v_add_lshl_u32 v9, v9, v5, 1
	v_lshlrev_b32_e32 v8, 1, v7
	v_lshrrev_b32_e32 v10, 2, v7
	v_and_or_b32 v11, v7, s1, v11
	v_lshl_add_u32 v130, v7, 12, v9
	v_add_u32_e32 v7, 0x2000, v6
	v_ashrrev_i32_e32 v6, 31, v7
	v_lshrrev_b32_e32 v6, 22, v6
	v_and_b32_e32 v8, 24, v8
	v_and_b32_e32 v10, 4, v10
	v_add_u32_e32 v6, v7, v6
	v_or3_b32 v8, v11, v10, v8
	v_ashrrev_i32_e32 v6, 10, v6
	v_lshl_add_u32 v194, v8, 12, v9
	v_mul_i32_i24_e32 v8, 0x400, v6
	v_sub_u32_e32 v7, v7, v8
	v_lshrrev_b32_e32 v8, 4, v7
	v_bitop3_b32 v8, v8, v7, 32 bitop3:0x6c
	v_lshlrev_b32_e32 v7, 3, v6
	v_and_b32_e32 v9, -16, v7
	v_ashrrev_i32_e32 v7, 31, v8
	v_lshrrev_b32_e32 v7, 26, v7
	v_add_u32_e32 v10, v8, v7
	v_ashrrev_i32_e32 v7, 6, v10
	v_add_u32_e32 v9, v7, v9
	v_and_b32_e32 v10, 0xc0, v10
	v_and_b32_e32 v13, 3, v7
	v_sub_u32_e32 v8, v8, v10
	v_and_or_b32 v13, v9, s1, v13
	s_ashr_i32 s1, s12, 6
	v_lshlrev_b32_e32 v11, 5, v6
	v_ashrrev_i16_sdwa v8, v231, sext(v8) dst_sel:DWORD dst_unused:UNUSED_PAD src0_sel:DWORD src1_sel:BYTE_0
	v_lshlrev_b32_e32 v10, 1, v9
	v_lshrrev_b32_e32 v12, 2, v9
	s_lshl_b32 s55, s1, 10
	v_and_b32_e32 v11, 32, v11
	v_bfe_i32 v8, v8, 0, 16
	v_and_b32_e32 v10, 24, v10
	v_and_b32_e32 v12, 4, v12
	s_add_i32 s83, s55, 0x10000
	v_or3_b32 v10, v13, v12, v10
	v_add_lshl_u32 v11, v11, v8, 1
	s_mov_b32 m0, s83
	s_add_i32 s54, s55, 0x12000
	s_ashr_i32 s0, s12, 8
	v_lshl_add_u32 v134, v10, 12, v11
	global_load_lds_dwordx4 v194, s[52:53]
	s_mov_b32 m0, s54
	s_add_i32 s34, s55, 0x2000
	global_load_lds_dwordx4 v134, s[52:53]
	s_mov_b32 m0, s55
	s_add_u32 s8, s52, 0x80000
	v_lshl_add_u32 v132, v9, 12, v11
	global_load_lds_dwordx4 v130, s[6:7]
	s_mov_b32 m0, s34
	s_addc_u32 s9, s53, 0
	s_add_i32 s4, s55, 0x14000
	global_load_lds_dwordx4 v132, s[6:7]
	s_mov_b32 m0, s4
	s_add_i32 s5, s55, 0x16000
	global_load_lds_dwordx4 v194, s[8:9]
	s_mov_b32 m0, s5
	v_writelane_b32 v250, s25, 25
	global_load_lds_dwordx4 v134, s[8:9]
	s_add_u32 s8, s6, 0x80000
	s_addc_u32 s9, s7, 0
	s_add_i32 s56, s55, 0x4000
	s_mov_b32 m0, s56
	s_add_i32 s57, s55, 0x6000
	global_load_lds_dwordx4 v130, s[8:9]
	s_mov_b32 m0, s57
	s_cmp_lg_u32 s0, 1
	global_load_lds_dwordx4 v132, s[8:9]
	s_mov_b32 s3, 0x340000
	s_mov_b32 s20, 0x480000
	s_mov_b32 s21, 0x510000
	s_mov_b32 s22, 0x5a0000
	s_mov_b32 s23, 0x630000
	s_mov_b32 s24, 0x68000
	s_mov_b32 s25, 0xd0000
	s_mov_b32 s27, 0x138000
	v_writelane_b32 v250, s12, 26
	s_setprio 1
	s_cbranch_scc1 .LBB0_127
	s_barrier
	s_setprio 0

.LBB0_196:
	s_or_b64 exec, exec, s[0:1]
	s_and_b64 s[0:1], s[22:23], exec
	s_movk_i32 s0, 0x240
	s_cselect_b32 s33, s0, 0x200
	v_mov_b32_e32 v2, v1
	s_cmp_lt_i32 s92, s33
	s_cselect_b64 s[86:87], -1, 0
	s_cmp_ge_i32 s92, s33
	v_readfirstlane_b32 s4, v2
	s_cbranch_scc1 .LBB0_212
	v_lshlrev_b32_e32 v3, 4, v2
	v_add_u32_e32 v4, 0x2000, v3
	v_ashrrev_i32_e32 v5, 31, v4
	v_lshrrev_b32_e32 v5, 22, v5
	v_add_u32_e32 v5, v4, v5
	v_ashrrev_i32_e32 v5, 10, v5
	v_mul_i32_i24_e32 v6, 0x400, v5
	v_sub_u32_e32 v4, v4, v6
	v_lshrrev_b32_e32 v6, 4, v4
	v_bitop3_b32 v4, v6, v4, 32 bitop3:0x6c
	v_ashrrev_i32_e32 v6, 31, v4
	v_lshrrev_b32_e32 v6, 26, v6
	v_add_u32_e32 v6, v4, v6
	v_lshlrev_b32_e32 v8, 3, v5
	v_ashrrev_i32_e32 v7, 6, v6
	v_and_b32_e32 v8, -16, v8
	v_add_u32_e32 v8, v7, v8
	v_and_b32_e32 v7, 3, v7
	s_mov_b32 s1, 0x3fffe0
	v_lshrrev_b32_e32 v9, 2, v8
	v_lshlrev_b32_e32 v10, 1, v8
	v_and_b32_e32 v6, 0xc0, v6
	v_and_or_b32 v7, v8, s1, v7
	v_and_b32_e32 v9, 4, v9
	v_and_b32_e32 v10, 24, v10
	v_lshlrev_b32_e32 v5, 5, v5
	v_sub_u32_e32 v4, v4, v6
	v_or3_b32 v7, v7, v9, v10
	v_and_b32_e32 v5, 32, v5
	v_ashrrev_i16_sdwa v4, v231, sext(v4) dst_sel:DWORD dst_unused:UNUSED_PAD src0_sel:DWORD src1_sel:BYTE_0
	v_mul_u32_u24_e32 v7, 0x3400, v7
	v_add_u32_sdwa v4, v5, sext(v4) dst_sel:DWORD dst_unused:UNUSED_PAD src0_sel:DWORD src1_sel:WORD_0
	v_lshlrev_b32_e32 v5, 9, v8
	v_add_lshl_u32 v130, v7, v4, 1
	v_lshl_add_u32 v132, v4, 1, v5
	v_bfe_i32 v4, v2, 27, 1
	v_lshrrev_b32_e32 v4, 22, v4
	v_add_u32_e32 v4, v3, v4
	v_and_b32_e32 v4, 0xfffffc00, v4
	v_sub_u32_e32 v3, v3, v4
	v_lshrrev_b32_e32 v4, 4, v3
	v_ashrrev_i32_e32 v6, 31, v2
	v_bitop3_b32 v3, v4, v3, 32 bitop3:0x6c
	v_lshrrev_b32_e32 v6, 26, v6
	v_ashrrev_i32_e32 v4, 31, v3
	v_add_u32_e32 v6, v2, v6
	v_lshrrev_b32_e32 v4, 26, v4
	v_ashrrev_i32_e32 v6, 6, v6
	v_add_u32_e32 v4, v3, v4
	v_lshlrev_b32_e32 v7, 3, v6
	v_ashrrev_i32_e32 v5, 6, v4
	v_and_b32_e32 v7, -16, v7
	v_add_u32_e32 v7, v5, v7
	v_and_b32_e32 v5, 3, v5
	v_lshrrev_b32_e32 v8, 2, v7
	v_lshlrev_b32_e32 v9, 1, v7
	v_and_b32_e32 v4, 0xc0, v4
	s_ashr_i32 s0, s4, 6
	v_and_or_b32 v5, v7, s1, v5
	v_and_b32_e32 v8, 4, v8
	v_and_b32_e32 v9, 24, v9
	v_lshlrev_b32_e32 v6, 5, v6
	v_sub_u32_e32 v3, v3, v4
	s_lshl_b32 s5, s0, 10
	v_or3_b32 v5, v5, v8, v9
	v_and_b32_e32 v6, 32, v6
	v_ashrrev_i16_sdwa v3, v231, sext(v3) dst_sel:DWORD dst_unused:UNUSED_PAD src0_sel:DWORD src1_sel:BYTE_0
	v_mul_u32_u24_e32 v5, 0x3400, v5
	v_add_u32_sdwa v3, v6, sext(v3) dst_sel:DWORD dst_unused:UNUSED_PAD src0_sel:DWORD src1_sel:WORD_0
	s_add_i32 s12, s5, 0x10000
	v_readlane_b32 s6, v251, 0
	v_add_lshl_u32 v134, v5, v3, 1
	s_mov_b32 m0, s12
	v_readlane_b32 s7, v251, 1
	s_add_i32 s17, s5, 0x12000
	v_lshlrev_b32_e32 v4, 9, v7
	v_lshl_add_u32 v136, v3, 1, v4
	s_add_i32 s26, s5, 0x2000
	s_add_i32 s34, s5, 0x14000
	global_load_lds_dwordx4 v134, s[6:7]
	s_mov_b32 m0, s17
	s_add_i32 s35, s5, 0x16000
	global_load_lds_dwordx4 v130, s[6:7]
	v_readlane_b32 s6, v251, 4
	s_mov_b32 m0, s5
	v_readlane_b32 s7, v251, 5
	s_add_i32 s56, s5, 0x4000
	s_add_i32 s57, s5, 0x6000
	s_ashr_i32 s1, s4, 8
	s_mov_b64 s[20:21], s[86:87]
	s_cmp_lg_u32 s1, 1
	global_load_lds_dwordx4 v136, s[6:7]
	s_mov_b32 m0, s26
	s_nop 0
	global_load_lds_dwordx4 v132, s[6:7]
	v_readlane_b32 s6, v251, 2
	s_mov_b32 m0, s34
	v_readlane_b32 s7, v251, 3
	s_nop 4
	global_load_lds_dwordx4 v134, s[6:7]
	s_mov_b32 m0, s35
	s_nop 0
	global_load_lds_dwordx4 v130, s[6:7]
	v_readlane_b32 s6, v251, 6
	s_mov_b32 m0, s56
	v_readlane_b32 s7, v251, 7
	s_nop 4
	global_load_lds_dwordx4 v136, s[6:7]
	s_mov_b32 m0, s57
	s_nop 0
	global_load_lds_dwordx4 v132, s[6:7]
	s_setprio 1
	s_cbranch_scc1 .LBB0_199
	s_barrier
	s_setprio 0

.LBB0_248:
	s_or_b64 exec, exec, s[0:1]
	v_readlane_b32 s0, v251, 14
	v_mov_b32_e32 v8, v1
	v_readlane_b32 s1, v251, 15
	s_andn2_b64 vcc, exec, s[0:1]
	v_readfirstlane_b32 s4, v8
	s_cbranch_vccnz .LBB0_260
	v_lshlrev_b32_e32 v6, 4, v8
	v_add_u32_e32 v3, 0x2000, v6
	v_ashrrev_i32_e32 v2, 31, v3
	v_lshrrev_b32_e32 v2, 22, v2
	v_add_u32_e32 v2, v3, v2
	v_ashrrev_i32_e32 v2, 10, v2
	v_lshlrev_b32_e32 v4, 5, v2
	v_and_b32_e32 v5, 32, v4
	v_mul_i32_i24_e32 v4, 0x400, v2
	v_sub_u32_e32 v3, v3, v4
	v_lshrrev_b32_e32 v4, 4, v3
	v_bitop3_b32 v4, v4, v3, 32 bitop3:0x6c
	v_ashrrev_i32_e32 v3, 31, v4
	v_lshrrev_b32_e32 v3, 26, v3
	v_add_u32_e32 v7, v4, v3
	v_ashrrev_i32_e32 v3, 6, v7
	v_and_b32_e32 v7, 0xc0, v7
	v_sub_u32_e32 v4, v4, v7
	v_lshlrev_b32_e32 v7, 3, v2
	v_and_b32_e32 v7, -16, v7
	v_add_u32_e32 v7, v3, v7
	v_ashrrev_i16_sdwa v4, v231, sext(v4) dst_sel:DWORD dst_unused:UNUSED_PAD src0_sel:DWORD src1_sel:BYTE_0
	v_and_b32_e32 v9, 3, v3
	s_mov_b32 s1, 0x7ffe0
	v_lshrrev_b32_e32 v10, 2, v7
	v_lshlrev_b32_e32 v11, 1, v7
	v_bfe_i32 v4, v4, 0, 16
	v_and_or_b32 v9, v7, s1, v9
	v_and_b32_e32 v10, 4, v10
	v_and_b32_e32 v11, 24, v11
	v_or3_b32 v9, v9, v10, v11
	v_add_lshl_u32 v5, v5, v4, 1
	v_lshl_add_u32 v158, v9, 13, v5
	v_lshl_add_u32 v160, v7, 13, v5
	v_ashrrev_i32_e32 v5, 31, v8
	v_lshrrev_b32_e32 v5, 26, v5
	v_add_u32_e32 v5, v8, v5
	v_ashrrev_i32_e32 v5, 6, v5
	v_lshlrev_b32_e32 v7, 5, v5
	v_and_b32_e32 v9, 32, v7
	v_bfe_i32 v7, v8, 27, 1
	v_lshrrev_b32_e32 v7, 22, v7
	v_add_u32_e32 v7, v6, v7
	v_and_b32_e32 v7, 0xfffffc00, v7
	v_sub_u32_e32 v6, v6, v7
	v_lshrrev_b32_e32 v7, 4, v6
	v_bitop3_b32 v7, v7, v6, 32 bitop3:0x6c
	v_ashrrev_i32_e32 v6, 31, v7
	v_lshrrev_b32_e32 v6, 26, v6
	v_add_u32_e32 v10, v7, v6
	v_ashrrev_i32_e32 v6, 6, v10
	v_and_b32_e32 v10, 0xc0, v10
	v_sub_u32_e32 v7, v7, v10
	v_lshlrev_b32_e32 v10, 3, v5
	v_and_b32_e32 v10, -16, v10
	v_add_u32_e32 v10, v6, v10
	s_ashr_i32 s0, s4, 6
	v_ashrrev_i16_sdwa v7, v231, sext(v7) dst_sel:DWORD dst_unused:UNUSED_PAD src0_sel:DWORD src1_sel:BYTE_0
	v_and_b32_e32 v11, 3, v6
	v_lshrrev_b32_e32 v12, 2, v10
	v_lshlrev_b32_e32 v13, 1, v10
	s_lshl_b32 s5, s0, 10
	v_bfe_i32 v7, v7, 0, 16
	v_and_or_b32 v11, v10, s1, v11
	v_and_b32_e32 v12, 4, v12
	v_and_b32_e32 v13, 24, v13
	v_or3_b32 v11, v11, v12, v13
	v_add_lshl_u32 v9, v9, v7, 1
	s_add_i32 s12, s5, 0x10000
	v_readlane_b32 s6, v251, 27
	v_lshl_add_u32 v162, v11, 13, v9
	s_mov_b32 m0, s12
	v_readlane_b32 s7, v251, 28
	s_add_i32 s17, s5, 0x12000
	v_lshl_add_u32 v164, v10, 13, v9
	s_add_i32 s26, s5, 0x2000
	s_add_i32 s34, s5, 0x14000
	s_add_i32 s35, s5, 0x16000
	global_load_lds_dwordx4 v162, s[6:7]
	s_mov_b32 m0, s17
	s_add_i32 s42, s5, 0x4000
	global_load_lds_dwordx4 v158, s[6:7]
	v_readlane_b32 s6, v251, 23
	s_mov_b32 m0, s5
	v_readlane_b32 s7, v251, 24
	s_add_i32 s54, s5, 0x6000
	s_ashr_i32 s1, s4, 8
	s_cmp_lg_u32 s1, 1
	s_nop 1
	global_load_lds_dwordx4 v164, s[6:7]
	s_mov_b32 m0, s26
	s_nop 0
	global_load_lds_dwordx4 v160, s[6:7]
	v_readlane_b32 s6, v251, 21
	s_mov_b32 m0, s34
	v_readlane_b32 s7, v251, 22
	s_nop 4
	global_load_lds_dwordx4 v162, s[6:7]
	s_mov_b32 m0, s35
	s_nop 0
	global_load_lds_dwordx4 v158, s[6:7]
	v_readlane_b32 s6, v251, 25
	s_mov_b32 m0, s42
	v_readlane_b32 s7, v251, 26
	s_nop 4
	global_load_lds_dwordx4 v164, s[6:7]
	s_mov_b32 m0, s54
	s_nop 0
	global_load_lds_dwordx4 v160, s[6:7]
	s_setprio 1
	s_cbranch_scc1 .LBB0_251
	s_barrier
	s_setprio 0

.LBB0_260:
	v_cndmask_b32_e64 v2, 0, 1, s[22:23]
	v_cmp_ne_u32_e64 s[0:1], 1, v2
	s_andn2_b64 vcc, exec, s[22:23]
	s_movk_i32 s4, 0x1000
	v_writelane_b32 v250, s0, 27
	v_readlane_b32 s13, v251, 60
	s_nop 0
	v_writelane_b32 v250, s1, 28
	s_cbranch_vccnz .LBB0_272
	v_readlane_b32 s0, v251, 41
	v_mov_b32_e32 v8, v1
	v_readlane_b32 s1, v251, 42
	s_andn2_b64 vcc, exec, s[0:1]
	v_readfirstlane_b32 s12, v8
	s_cbranch_vccnz .LBB0_271
	v_lshlrev_b32_e32 v6, 4, v8
	v_add_u32_e32 v3, 0x2000, v6
	v_ashrrev_i32_e32 v2, 31, v3
	v_lshrrev_b32_e32 v2, 22, v2
	v_add_u32_e32 v2, v3, v2
	v_ashrrev_i32_e32 v2, 10, v2
	v_lshlrev_b32_e32 v4, 5, v2
	v_and_b32_e32 v5, 32, v4
	v_mul_i32_i24_e32 v4, 0x400, v2
	v_sub_u32_e32 v3, v3, v4
	v_lshrrev_b32_e32 v4, 4, v3
	v_bitop3_b32 v4, v4, v3, 32 bitop3:0x6c
	v_ashrrev_i32_e32 v3, 31, v4
	v_lshrrev_b32_e32 v3, 26, v3
	v_add_u32_e32 v7, v4, v3
	v_ashrrev_i32_e32 v3, 6, v7
	v_and_b32_e32 v7, 0xc0, v7
	v_sub_u32_e32 v4, v4, v7
	v_lshlrev_b32_e32 v7, 3, v2
	v_and_b32_e32 v7, -16, v7
	v_add_u32_e32 v7, v3, v7
	v_ashrrev_i16_sdwa v4, v231, sext(v4) dst_sel:DWORD dst_unused:UNUSED_PAD src0_sel:DWORD src1_sel:BYTE_0
	v_and_b32_e32 v9, 3, v3
	s_mov_b32 s1, 0x3fffe0
	v_lshrrev_b32_e32 v10, 2, v7
	v_lshlrev_b32_e32 v11, 1, v7
	v_bfe_i32 v4, v4, 0, 16
	v_and_or_b32 v9, v7, s1, v9
	v_and_b32_e32 v10, 4, v10
	v_and_b32_e32 v11, 24, v11
	v_or3_b32 v9, v9, v10, v11
	v_add_lshl_u32 v5, v5, v4, 1
	v_lshl_add_u32 v130, v9, 10, v5
	v_lshl_add_u32 v132, v7, 10, v5
	v_ashrrev_i32_e32 v5, 31, v8
	v_lshrrev_b32_e32 v5, 26, v5
	v_add_u32_e32 v5, v8, v5
	v_ashrrev_i32_e32 v5, 6, v5
	v_lshlrev_b32_e32 v7, 5, v5
	v_and_b32_e32 v9, 32, v7
	v_bfe_i32 v7, v8, 27, 1
	v_lshrrev_b32_e32 v7, 22, v7
	v_add_u32_e32 v7, v6, v7
	v_and_b32_e32 v7, 0xfffffc00, v7
	v_sub_u32_e32 v6, v6, v7
	v_lshrrev_b32_e32 v7, 4, v6
	v_bitop3_b32 v7, v7, v6, 32 bitop3:0x6c
	v_ashrrev_i32_e32 v6, 31, v7
	v_lshrrev_b32_e32 v6, 26, v6
	v_add_u32_e32 v10, v7, v6
	v_ashrrev_i32_e32 v6, 6, v10
	v_and_b32_e32 v10, 0xc0, v10
	v_sub_u32_e32 v7, v7, v10
	v_lshlrev_b32_e32 v10, 3, v5
	v_and_b32_e32 v10, -16, v10
	v_add_u32_e32 v10, v6, v10
	s_ashr_i32 s0, s12, 6
	v_ashrrev_i16_sdwa v7, v231, sext(v7) dst_sel:DWORD dst_unused:UNUSED_PAD src0_sel:DWORD src1_sel:BYTE_0
	v_and_b32_e32 v11, 3, v6
	v_lshrrev_b32_e32 v12, 2, v10
	v_lshlrev_b32_e32 v13, 1, v10
	s_lshl_b32 s17, s0, 10
	v_bfe_i32 v7, v7, 0, 16
	v_and_or_b32 v11, v10, s1, v11
	v_and_b32_e32 v12, 4, v12
	v_and_b32_e32 v13, 24, v13
	v_or3_b32 v11, v11, v12, v13
	v_add_lshl_u32 v9, v9, v7, 1
	s_add_i32 s26, s17, 0x10000
	v_readlane_b32 s4, v251, 47
	v_lshl_add_u32 v134, v11, 10, v9
	s_mov_b32 m0, s26
	v_readlane_b32 s5, v251, 48
	s_add_i32 s34, s17, 0x12000
	v_lshl_add_u32 v136, v10, 10, v9
	s_add_i32 s35, s17, 0x2000
	s_add_i32 s42, s17, 0x14000
	s_add_i32 s56, s17, 0x16000
	global_load_lds_dwordx4 v134, s[4:5]
	s_mov_b32 m0, s34
	s_add_i32 s57, s17, 0x4000
	global_load_lds_dwordx4 v130, s[4:5]
	s_mov_b32 m0, s17
	v_readlane_b32 s4, v251, 45
	global_load_lds_dwordx4 v136, s[18:19]
	s_mov_b32 m0, s35
	v_readlane_b32 s5, v251, 46
	global_load_lds_dwordx4 v132, s[18:19]
	s_mov_b32 m0, s42
	s_add_i32 s58, s17, 0x6000
	s_ashr_i32 s1, s12, 8
	s_nop 0
	global_load_lds_dwordx4 v134, s[4:5]
	s_mov_b32 m0, s56
	s_cmp_lg_u32 s1, 1
	global_load_lds_dwordx4 v130, s[4:5]
	v_readlane_b32 s4, v251, 31
	s_mov_b32 m0, s57
	v_readlane_b32 s5, v251, 32
	s_nop 4
	global_load_lds_dwordx4 v136, s[4:5]
	s_mov_b32 m0, s58
	s_nop 0
	global_load_lds_dwordx4 v132, s[4:5]
	s_setprio 1
	s_cbranch_scc1 .LBB0_264
	s_barrier
	s_setprio 0

.LBB0_359:
	s_and_b64 vcc, exec, s[22:23]
	s_cbranch_vccnz .LBB0_471
	v_bfe_i32 v4, v2, 27, 1
	v_lshlrev_b32_e32 v6, 4, v2
	v_lshrrev_b32_e32 v4, 22, v4
	v_ashrrev_i32_e32 v3, 31, v2
	v_add_u32_e32 v4, v6, v4
	v_lshrrev_b32_e32 v3, 26, v3
	v_and_b32_e32 v4, 0xfffffc00, v4
	v_add_u32_e32 v3, v2, v3
	v_sub_u32_e32 v4, v6, v4
	v_ashrrev_i32_e32 v3, 6, v3
	v_lshrrev_b32_e32 v5, 4, v4
	v_bitop3_b32 v5, v5, v4, 32 bitop3:0x6c
	v_lshlrev_b32_e32 v4, 3, v3
	v_and_b32_e32 v7, -16, v4
	v_ashrrev_i32_e32 v4, 31, v5
	v_lshrrev_b32_e32 v4, 26, v4
	v_add_u32_e32 v8, v5, v4
	v_ashrrev_i32_e32 v4, 6, v8
	v_and_b32_e32 v8, 0xc0, v8
	v_sub_u32_e32 v5, v5, v8
	v_lshlrev_b32_e32 v9, 5, v3
	v_ashrrev_i16_sdwa v5, v231, sext(v5) dst_sel:DWORD dst_unused:UNUSED_PAD src0_sel:DWORD src1_sel:BYTE_0
	v_and_b32_e32 v9, 32, v9
	v_bfe_i32 v5, v5, 0, 16
	v_add_u32_e32 v7, v4, v7
	v_and_b32_e32 v11, 3, v4
	s_mov_b32 s1, 0x1fffe0
	v_add_lshl_u32 v9, v9, v5, 1
	v_lshlrev_b32_e32 v8, 1, v7
	v_lshrrev_b32_e32 v10, 2, v7
	v_and_or_b32 v11, v7, s1, v11
	v_lshl_add_u32 v206, v7, 11, v9
	v_add_u32_e32 v7, 0x2000, v6
	v_ashrrev_i32_e32 v6, 31, v7
	v_lshrrev_b32_e32 v6, 22, v6
	v_and_b32_e32 v8, 24, v8
	v_and_b32_e32 v10, 4, v10
	v_add_u32_e32 v6, v7, v6
	v_or3_b32 v8, v11, v10, v8
	v_ashrrev_i32_e32 v6, 10, v6
	v_lshl_add_u32 v194, v8, 11, v9
	v_mul_i32_i24_e32 v8, 0x400, v6
	v_sub_u32_e32 v7, v7, v8
	v_lshrrev_b32_e32 v8, 4, v7
	v_bitop3_b32 v8, v8, v7, 32 bitop3:0x6c
	v_lshlrev_b32_e32 v7, 3, v6
	v_and_b32_e32 v9, -16, v7
	v_ashrrev_i32_e32 v7, 31, v8
	v_lshrrev_b32_e32 v7, 26, v7
	v_add_u32_e32 v10, v8, v7
	v_ashrrev_i32_e32 v7, 6, v10
	v_add_u32_e32 v9, v7, v9
	v_and_b32_e32 v10, 0xc0, v10
	v_and_b32_e32 v13, 3, v7
	v_sub_u32_e32 v8, v8, v10
	v_and_or_b32 v13, v9, s1, v13
	s_ashr_i32 s1, s10, 6
	v_lshlrev_b32_e32 v11, 5, v6
	v_ashrrev_i16_sdwa v8, v231, sext(v8) dst_sel:DWORD dst_unused:UNUSED_PAD src0_sel:DWORD src1_sel:BYTE_0
	v_lshlrev_b32_e32 v10, 1, v9
	v_lshrrev_b32_e32 v12, 2, v9
	s_lshl_b32 s34, s1, 10
	v_and_b32_e32 v11, 32, v11
	v_bfe_i32 v8, v8, 0, 16
	v_and_b32_e32 v10, 24, v10
	v_and_b32_e32 v12, 4, v12
	s_add_i32 s35, s34, 0x10000
	v_or3_b32 v10, v13, v12, v10
	v_add_lshl_u32 v11, v11, v8, 1
	s_mov_b32 m0, s35
	s_add_i32 s42, s34, 0x12000
	s_ashr_i32 s0, s10, 8
	v_lshl_add_u32 v210, v10, 11, v11
	global_load_lds_dwordx4 v194, s[52:53]
	s_mov_b32 m0, s42
	s_add_i32 s56, s34, 0x2000
	global_load_lds_dwordx4 v210, s[52:53]
	s_mov_b32 m0, s34
	s_add_u32 s4, s52, 0x40000
	v_lshl_add_u32 v208, v9, 11, v11
	global_load_lds_dwordx4 v206, s[8:9]
	s_mov_b32 m0, s56
	s_addc_u32 s5, s53, 0
	s_add_i32 s57, s34, 0x14000
	global_load_lds_dwordx4 v208, s[8:9]
	s_mov_b32 m0, s57
	s_add_i32 s67, s34, 0x16000
	global_load_lds_dwordx4 v194, s[4:5]
	s_mov_b32 m0, s67
	s_mov_b32 s27, s10
	global_load_lds_dwordx4 v210, s[4:5]
	s_add_u32 s4, s8, 0x40000
	s_addc_u32 s5, s9, 0
	s_add_i32 s70, s34, 0x4000
	s_mov_b32 m0, s70
	s_add_i32 s71, s34, 0x6000
	global_load_lds_dwordx4 v206, s[4:5]
	s_mov_b32 m0, s71
	s_cmp_lg_u32 s0, 1
	global_load_lds_dwordx4 v208, s[4:5]
	s_setprio 1
	s_cbranch_scc1 .LBB0_362
	s_barrier
	s_setprio 0

.LBB0_497:
	s_or_b64 exec, exec, s[0:1]
	v_mov_b32_e32 v8, v1
	s_and_b64 vcc, exec, s[22:23]
	v_readfirstlane_b32 s12, v8
	s_cbranch_vccnz .LBB0_509
	v_lshlrev_b32_e32 v5, 4, v8
	v_add_u32_e32 v3, 0x2000, v5
	v_ashrrev_i32_e32 v2, 31, v3
	v_lshrrev_b32_e32 v2, 22, v2
	v_add_u32_e32 v2, v3, v2
	v_ashrrev_i32_e32 v2, 10, v2
	v_mul_i32_i24_e32 v4, 0x400, v2
	v_sub_u32_e32 v3, v3, v4
	v_lshrrev_b32_e32 v4, 4, v3
	v_bitop3_b32 v4, v4, v3, 32 bitop3:0x6c
	v_ashrrev_i32_e32 v3, 31, v4
	v_lshrrev_b32_e32 v3, 26, v3
	s_mov_b32 s25, s43
	v_add_u32_e32 v6, v4, v3
	v_lshlrev_b32_e32 v7, 3, v2
	s_lshl_b64 s[0:1], s[24:25], 23
	v_readlane_b32 s4, v251, 39
	v_ashrrev_i32_e32 v3, 6, v6
	v_and_b32_e32 v7, -16, v7
	s_add_u32 s17, s4, s0
	v_readlane_b32 s0, v251, 40
	v_add_u32_e32 v7, v3, v7
	s_addc_u32 s83, s0, s1
	v_and_b32_e32 v9, 3, v3
	s_mov_b32 s0, 0xfffe0
	v_lshrrev_b32_e32 v10, 2, v7
	v_lshlrev_b32_e32 v11, 1, v7
	v_and_b32_e32 v6, 0xc0, v6
	v_and_or_b32 v9, v7, s0, v9
	v_and_b32_e32 v10, 4, v10
	v_and_b32_e32 v11, 24, v11
	v_sub_u32_e32 v4, v4, v6
	v_or3_b32 v9, v9, v10, v11
	v_lshlrev_b32_e32 v10, 5, v2
	v_ashrrev_i16_sdwa v4, v231, sext(v4) dst_sel:DWORD dst_unused:UNUSED_PAD src0_sel:DWORD src1_sel:BYTE_0
	v_and_b32_e32 v10, 32, v10
	v_bfe_i32 v4, v4, 0, 16
	v_add_lshl_u32 v6, v10, v4, 1
	v_lshl_add_u32 v138, v9, 12, v6
	v_lshl_add_u32 v140, v7, 12, v6
	v_bfe_i32 v6, v8, 27, 1
	v_lshrrev_b32_e32 v6, 22, v6
	v_add_u32_e32 v6, v5, v6
	v_and_b32_e32 v6, 0xfffffc00, v6
	v_sub_u32_e32 v5, v5, v6
	v_lshrrev_b32_e32 v6, 4, v5
	v_bitop3_b32 v7, v6, v5, 32 bitop3:0x6c
	v_ashrrev_i32_e32 v6, 31, v8
	v_lshrrev_b32_e32 v6, 26, v6
	v_ashrrev_i32_e32 v5, 31, v7
	v_add_u32_e32 v6, v8, v6
	v_lshrrev_b32_e32 v5, 26, v5
	v_ashrrev_i32_e32 v6, 6, v6
	v_add_u32_e32 v9, v7, v5
	v_lshlrev_b32_e32 v10, 3, v6
	v_ashrrev_i32_e32 v5, 6, v9
	v_and_b32_e32 v10, -16, v10
	v_add_u32_e32 v10, v5, v10
	v_and_b32_e32 v11, 3, v5
	v_and_or_b32 v11, v10, s0, v11
	s_lshr_b32 s56, s33, 3
	v_readlane_b32 s0, v252, 60
	s_or_b32 s0, s56, s0
	v_readlane_b32 s5, v252, 59
	s_mul_i32 s0, s0, s5
	v_readlane_b32 s5, v252, 58
	s_add_i32 s0, s0, s5
	s_ashr_i32 s5, s0, 31
	s_lshr_b32 s5, s5, 26
	v_lshrrev_b32_e32 v12, 2, v10
	v_lshlrev_b32_e32 v13, 1, v10
	v_and_b32_e32 v9, 0xc0, v9
	s_add_i32 s5, s0, s5
	v_and_b32_e32 v12, 4, v12
	v_and_b32_e32 v13, 24, v13
	v_sub_u32_e32 v7, v7, v9
	s_ashr_i32 s6, s5, 6
	v_or3_b32 v11, v11, v12, v13
	v_lshlrev_b32_e32 v12, 5, v6
	v_ashrrev_i16_sdwa v7, v231, sext(v7) dst_sel:DWORD dst_unused:UNUSED_PAD src0_sel:DWORD src1_sel:BYTE_0
	s_lshl_b32 s8, s6, 3
	v_and_b32_e32 v12, 32, v12
	v_bfe_i32 v7, v7, 0, 16
	s_sub_i32 s6, s56, s8
	v_add_lshl_u32 v9, v12, v7, 1
	s_min_i32 s9, s6, 8
	v_lshl_add_u32 v194, v11, 12, v9
	v_lshl_add_u32 v142, v10, 12, v9
	v_cvt_f32_i32_e32 v9, s9
	s_andn2_b32 s5, s5, 63
	s_sub_i32 s5, s0, s5
	v_cvt_f32_i32_e32 v10, s5
	v_rcp_iflag_f32_e32 v11, v9
	s_xor_b32 s0, s5, s9
	s_ashr_i32 s1, s12, 6
	s_ashr_i32 s0, s0, 30
	v_mul_f32_e32 v11, v10, v11
	v_trunc_f32_e32 v11, v11
	v_fma_f32 v10, -v11, v9, v10
	v_cvt_i32_f32_e32 v11, v11
	s_ashr_i32 s4, s12, 8
	s_lshl_b32 s42, s1, 10
	s_or_b32 s0, s0, 1
	v_cmp_ge_f32_e64 s[6:7], |v10|, |v9|
	s_and_b64 s[6:7], s[6:7], exec
	s_cselect_b32 s0, s0, 0
	v_readfirstlane_b32 s6, v11
	s_add_i32 s0, s6, s0
	s_mul_i32 s6, s0, s9
	s_sub_i32 s5, s5, s6
	s_sext_i32_i8 s5, s5
	s_add_i32 s40, s8, s5
	s_ashr_i32 s41, s40, 31
	s_lshl_b64 s[6:7], s[40:41], 20
	s_add_u32 s52, s96, s6
	s_addc_u32 s53, s97, s7
	s_bfe_i64 s[6:7], s[0:1], 0x80000
	s_lshl_b64 s[6:7], s[6:7], 20
	s_add_u32 s54, s17, s6
	s_addc_u32 s55, s83, s7
	s_add_i32 s41, s42, 0x10000
	s_mov_b32 m0, s41
	s_add_i32 s57, s42, 0x12000
	global_load_lds_dwordx4 v194, s[54:55]
	s_mov_b32 m0, s57
	s_add_i32 s58, s42, 0x2000
	global_load_lds_dwordx4 v138, s[54:55]
	s_mov_b32 m0, s42
	s_add_u32 s6, s54, 0x80000
	global_load_lds_dwordx4 v142, s[52:53]
	s_mov_b32 m0, s58
	s_addc_u32 s7, s55, 0
	s_add_i32 s59, s42, 0x14000
	global_load_lds_dwordx4 v140, s[52:53]
	s_mov_b32 m0, s59
	s_add_i32 s60, s42, 0x16000
	global_load_lds_dwordx4 v194, s[6:7]
	s_mov_b32 m0, s60
	s_nop 0
	global_load_lds_dwordx4 v138, s[6:7]
	s_add_u32 s6, s52, 0x80000
	s_addc_u32 s7, s53, 0
	s_add_i32 s61, s42, 0x4000
	s_mov_b32 m0, s61
	s_add_i32 s62, s42, 0x6000
	global_load_lds_dwordx4 v142, s[6:7]
	s_mov_b32 m0, s62
	s_cmp_lg_u32 s4, 1
	global_load_lds_dwordx4 v140, s[6:7]
	s_setprio 1
	s_cbranch_scc1 .LBB0_500
	s_barrier
	s_setprio 0
